# cache policy: the merged-branch output stores of P8 (512-byte wave stores) also non-temporal
# speedup vs baseline: 1.0292x; 1.0292x over previous
.LBB0_1145:
	s_waitcnt vmcnt(0)
	v_fmamk_f32 v218, v218, 0x3a800000, v228
	v_mul_f32_e32 v219, 0x4b800000, v218
	v_cmp_gt_f32_e32 vcc, s69, v218
	s_lshl_b32 s8, s50, 2
	s_or_b32 s8, s8, s64
	v_cndmask_b32_e32 v218, v218, v219, vcc
	v_rsq_f32_e32 v218, v218
	s_ashr_i32 s9, s8, 31
	s_lshl_b32 s12, s48, 1
	s_ashr_i32 s13, s12, 31
	v_mul_f32_e32 v219, 0x45800000, v218
	v_cndmask_b32_e32 v230, v218, v219, vcc
	v_mul_f32_e64 v220, v126, -v230
	v_mul_f32_e32 v220, 0x3fb8aa3b, v220
	v_mul_f32_e64 v231, v122, -v230
	v_exp_f32_e32 v220, v220
	v_mul_f32_e32 v231, 0x3fb8aa3b, v231
	v_exp_f32_e32 v231, v231
	v_mul_f32_e64 v241, v123, -v230
	v_add_f32_e32 v220, 1.0, v220
	v_rcp_f32_e32 v240, v220
	v_add_f32_e32 v220, 1.0, v231
	v_mul_f32_e64 v231, v127, -v230
	v_mul_f32_e32 v231, 0x3fb8aa3b, v231
	v_exp_f32_e32 v231, v231
	v_mul_f32_e32 v241, 0x3fb8aa3b, v241
	v_exp_f32_e32 v243, v241
	v_rcp_f32_e32 v242, v220
	v_add_f32_e32 v220, 1.0, v231
	v_mul_f32_e64 v231, v128, -v230
	v_rcp_f32_e32 v241, v220
	v_add_f32_e32 v220, 1.0, v243
	v_mul_f32_e32 v231, 0x3fb8aa3b, v231
	v_mul_f32_e64 v243, v124, -v230
	v_exp_f32_e32 v231, v231
	v_mul_f32_e32 v243, 0x3fb8aa3b, v243
	v_exp_f32_e32 v245, v243
	v_rcp_f32_e32 v243, v220
	v_add_f32_e32 v220, 1.0, v231
	v_mul_f32_e64 v231, v129, -v230
	v_rcp_f32_e32 v244, v220
	v_add_f32_e32 v220, 1.0, v245
	v_mul_f32_e32 v231, 0x3fb8aa3b, v231
	v_mul_f32_e64 v245, v125, -v230
	v_exp_f32_e32 v231, v231
	v_mul_f32_e32 v245, 0x3fb8aa3b, v245
	v_exp_f32_e32 v247, v245
	s_lshl_b64 s[8:9], s[8:9], 22
	s_add_u32 s34, s56, s8
	s_addc_u32 s35, s57, s9
	s_lshl_b64 s[8:9], s[12:13], 14
	v_rcp_f32_e32 v246, v220
	v_add_f32_e32 v220, 1.0, v231
	s_add_u32 s43, s34, s8
	v_rcp_f32_e32 v245, v220
	v_add_f32_e32 v220, 1.0, v247
	s_addc_u32 s41, s35, s9
	s_lshl_b64 s[8:9], s[28:29], 1
	v_rcp_f32_e32 v247, v220
	s_add_u32 s8, s43, s8
	s_addc_u32 s9, s41, s9
	v_lshlrev_b32_e32 v232, 16, v190
	v_and_b32_e32 v233, 0xffff0000, v190
	v_lshlrev_b32_e32 v190, 16, v191
	v_and_b32_e32 v191, 0xffff0000, v191
	v_lshlrev_b32_e32 v234, 16, v192
	v_and_b32_e32 v235, 0xffff0000, v192
	v_lshlrev_b32_e32 v192, 16, v193
	v_and_b32_e32 v193, 0xffff0000, v193
	v_lshlrev_b32_e32 v236, 16, v186
	v_and_b32_e32 v237, 0xffff0000, v186
	v_lshlrev_b32_e32 v186, 16, v187
	v_and_b32_e32 v187, 0xffff0000, v187
	v_lshlrev_b32_e32 v238, 16, v188
	v_and_b32_e32 v239, 0xffff0000, v188
	v_lshlrev_b32_e32 v188, 16, v189
	v_and_b32_e32 v189, 0xffff0000, v189
	s_cmp_gt_i32 s72, 1
	v_lshl_add_u64 v[218:219], v[200:201], 1, s[8:9]
	v_pk_fma_f32 v[232:233], v[240:241], v[232:233], v[236:237]
	v_pk_fma_f32 v[234:235], v[242:243], v[234:235], v[238:239]
	v_pk_fma_f32 v[190:191], v[244:245], v[190:191], v[186:187]
	v_pk_fma_f32 v[192:193], v[246:247], v[192:193], v[188:189]
	s_cselect_b64 s[12:13], -1, 0
	v_lshl_add_u64 v[218:219], v[202:203], 1, v[218:219]
	v_cvt_pk_bf16_f32 v186, v232, v233
	v_cvt_pk_bf16_f32 v187, v190, v191
	s_mov_b64 s[8:9], -1
	s_and_b64 vcc, exec, s[12:13]
	v_cvt_pk_bf16_f32 v188, v234, v235
	v_cvt_pk_bf16_f32 v189, v192, v193
	s_cbranch_vccz .LBB0_1147
	global_store_dwordx2 v[218:219], v[186:187], off nt
	global_store_dwordx2 v[218:219], v[188:189], off offset:512 nt
	s_mov_b64 s[8:9], 0

.LBB0_1149:
	v_mul_f32_e64 v220, v110, -v230
	v_mul_f32_e32 v220, 0x3fb8aa3b, v220
	v_mul_f32_e64 v231, v106, -v230
	v_exp_f32_e32 v220, v220
	v_mul_f32_e32 v231, 0x3fb8aa3b, v231
	v_exp_f32_e32 v231, v231
	v_mul_f32_e64 v233, v107, -v230
	v_add_f32_e32 v220, 1.0, v220
	v_rcp_f32_e32 v232, v220
	v_add_f32_e32 v220, 1.0, v231
	v_mul_f32_e64 v231, v111, -v230
	v_mul_f32_e32 v231, 0x3fb8aa3b, v231
	v_exp_f32_e32 v231, v231
	v_mul_f32_e32 v233, 0x3fb8aa3b, v233
	v_exp_f32_e32 v235, v233
	v_rcp_f32_e32 v234, v220
	v_add_f32_e32 v220, 1.0, v231
	v_mul_f32_e64 v231, v112, -v230
	v_mul_f32_e32 v231, 0x3fb8aa3b, v231
	v_exp_f32_e32 v231, v231
	v_rcp_f32_e32 v233, v220
	v_add_f32_e32 v220, 1.0, v235
	v_mul_f32_e64 v235, v108, -v230
	v_mul_f32_e32 v235, 0x3fb8aa3b, v235
	v_exp_f32_e32 v237, v235
	v_rcp_f32_e32 v235, v220
	v_add_f32_e32 v220, 1.0, v231
	v_mul_f32_e64 v231, v113, -v230
	v_mul_f32_e32 v231, 0x3fb8aa3b, v231
	v_mul_f32_e64 v230, v109, -v230
	v_exp_f32_e32 v231, v231
	v_mul_f32_e32 v230, 0x3fb8aa3b, v230
	v_exp_f32_e32 v238, v230
	v_rcp_f32_e32 v236, v220
	v_add_f32_e32 v220, 1.0, v237
	v_rcp_f32_e32 v230, v220
	v_add_f32_e32 v220, 1.0, v231
	v_rcp_f32_e32 v237, v220
	v_add_f32_e32 v220, 1.0, v238
	v_rcp_f32_e32 v231, v220
	v_lshlrev_b32_e32 v186, 16, v182
	v_and_b32_e32 v187, 0xffff0000, v182
	v_lshlrev_b32_e32 v182, 16, v183
	v_and_b32_e32 v183, 0xffff0000, v183
	v_lshlrev_b32_e32 v188, 16, v184
	v_and_b32_e32 v189, 0xffff0000, v184
	v_lshlrev_b32_e32 v184, 16, v185
	v_and_b32_e32 v185, 0xffff0000, v185
	v_lshlrev_b32_e32 v190, 16, v178
	v_and_b32_e32 v191, 0xffff0000, v178
	v_lshlrev_b32_e32 v178, 16, v179
	v_and_b32_e32 v179, 0xffff0000, v179
	v_lshlrev_b32_e32 v192, 16, v180
	v_and_b32_e32 v193, 0xffff0000, v180
	v_lshlrev_b32_e32 v180, 16, v181
	v_and_b32_e32 v181, 0xffff0000, v181
	v_pk_fma_f32 v[186:187], v[232:233], v[186:187], v[190:191]
	v_pk_fma_f32 v[188:189], v[234:235], v[188:189], v[192:193]
	v_pk_fma_f32 v[182:183], v[236:237], v[182:183], v[178:179]
	v_pk_fma_f32 v[184:185], v[230:231], v[184:185], v[180:181]
	v_cndmask_b32_e64 v178, 0, 1, s[12:13]
	s_mov_b64 s[34:35], -1
	v_cmp_ne_u32_e64 s[8:9], 1, v178
	s_andn2_b64 vcc, exec, s[12:13]
	v_cvt_pk_bf16_f32 v178, v186, v187
	v_cvt_pk_bf16_f32 v179, v182, v183
	v_cvt_pk_bf16_f32 v180, v188, v189
	v_cvt_pk_bf16_f32 v181, v184, v185
	s_cbranch_vccnz .LBB0_1151
	v_add_co_u32_e32 v182, vcc, 0x800000, v218
	s_mov_b64 s[34:35], 0
	s_nop 0
	v_addc_co_u32_e32 v183, vcc, 0, v219, vcc
	global_store_dwordx2 v[182:183], v[178:179], off nt
	global_store_dwordx2 v[182:183], v[180:181], off offset:512 nt

.LBB0_1153:
	s_nop 1
	v_fmamk_f32 v178, v229, 0x3a800000, v228
	v_mul_f32_e32 v179, 0x4b800000, v178
	v_cmp_gt_f32_e32 vcc, s69, v178
	s_lshl_b64 s[12:13], s[30:31], 1
	s_add_u32 s12, s43, s12
	v_cndmask_b32_e32 v178, v178, v179, vcc
	v_rsq_f32_e32 v178, v178
	s_addc_u32 s13, s41, s13
	v_lshlrev_b32_e32 v182, 16, v174
	v_and_b32_e32 v183, 0xffff0000, v174
	v_mul_f32_e32 v179, 0x45800000, v178
	v_cndmask_b32_e32 v180, v178, v179, vcc
	v_mul_f32_e64 v181, v118, -v180
	v_mul_f32_e32 v181, 0x3fb8aa3b, v181
	v_mul_f32_e64 v190, v114, -v180
	v_exp_f32_e32 v181, v181
	v_mul_f32_e32 v190, 0x3fb8aa3b, v190
	v_exp_f32_e32 v191, v190
	v_mul_f32_e64 v192, v115, -v180
	v_add_f32_e32 v181, 1.0, v181
	v_rcp_f32_e32 v190, v181
	v_add_f32_e32 v181, 1.0, v191
	v_mul_f32_e64 v191, v119, -v180
	v_mul_f32_e32 v191, 0x3fb8aa3b, v191
	v_exp_f32_e32 v191, v191
	v_mul_f32_e32 v192, 0x3fb8aa3b, v192
	v_exp_f32_e32 v193, v192
	v_rcp_f32_e32 v192, v181
	v_add_f32_e32 v181, 1.0, v191
	v_rcp_f32_e32 v191, v181
	v_add_f32_e32 v181, 1.0, v193
	v_mul_f32_e64 v193, v120, -v180
	v_mul_f32_e32 v193, 0x3fb8aa3b, v193
	v_exp_f32_e32 v220, v193
	v_mul_f32_e64 v193, v116, -v180
	v_mul_f32_e32 v193, 0x3fb8aa3b, v193
	v_exp_f32_e32 v229, v193
	v_rcp_f32_e32 v193, v181
	v_add_f32_e32 v181, 1.0, v220
	v_mul_f32_e64 v220, v121, -v180
	v_rcp_f32_e32 v230, v181
	v_add_f32_e32 v181, 1.0, v229
	v_mul_f32_e32 v220, 0x3fb8aa3b, v220
	v_mul_f32_e64 v229, v117, -v180
	v_exp_f32_e32 v220, v220
	v_mul_f32_e32 v229, 0x3fb8aa3b, v229
	v_exp_f32_e32 v229, v229
	v_rcp_f32_e32 v232, v181
	v_add_f32_e32 v181, 1.0, v220
	v_rcp_f32_e32 v231, v181
	v_add_f32_e32 v181, 1.0, v229
	v_rcp_f32_e32 v233, v181
	v_lshlrev_b32_e32 v174, 16, v175
	v_and_b32_e32 v175, 0xffff0000, v175
	v_lshlrev_b32_e32 v184, 16, v176
	v_and_b32_e32 v185, 0xffff0000, v176
	v_lshlrev_b32_e32 v176, 16, v177
	v_and_b32_e32 v177, 0xffff0000, v177
	v_lshlrev_b32_e32 v186, 16, v170
	v_and_b32_e32 v187, 0xffff0000, v170
	v_lshlrev_b32_e32 v170, 16, v171
	v_and_b32_e32 v171, 0xffff0000, v171
	v_lshlrev_b32_e32 v188, 16, v172
	v_and_b32_e32 v189, 0xffff0000, v172
	v_lshlrev_b32_e32 v172, 16, v173
	v_and_b32_e32 v173, 0xffff0000, v173
	v_lshl_add_u64 v[178:179], v[200:201], 1, s[12:13]
	v_pk_fma_f32 v[182:183], v[190:191], v[182:183], v[186:187]
	v_pk_fma_f32 v[184:185], v[192:193], v[184:185], v[188:189]
	v_pk_fma_f32 v[174:175], v[230:231], v[174:175], v[170:171]
	v_pk_fma_f32 v[176:177], v[232:233], v[176:177], v[172:173]
	v_lshl_add_u64 v[178:179], v[202:203], 1, v[178:179]
	v_cvt_pk_bf16_f32 v170, v182, v183
	v_cvt_pk_bf16_f32 v171, v174, v175
	s_mov_b64 s[12:13], -1
	s_and_b64 vcc, exec, s[8:9]
	v_cvt_pk_bf16_f32 v172, v184, v185
	v_cvt_pk_bf16_f32 v173, v176, v177
	s_cbranch_vccnz .LBB0_1155
	s_mov_b64 s[12:13], 0
	global_store_dwordx2 v[178:179], v[170:171], off nt
	global_store_dwordx2 v[178:179], v[172:173], off offset:512 nt

.LBB0_1157:
	v_mul_f32_e64 v181, v94, -v180
	v_mul_f32_e32 v181, 0x3fb8aa3b, v181
	v_mul_f32_e64 v182, v90, -v180
	v_exp_f32_e32 v181, v181
	v_mul_f32_e32 v182, 0x3fb8aa3b, v182
	v_exp_f32_e32 v183, v182
	v_mul_f32_e64 v184, v91, -v180
	v_add_f32_e32 v181, 1.0, v181
	v_rcp_f32_e32 v182, v181
	v_add_f32_e32 v181, 1.0, v183
	v_mul_f32_e64 v183, v95, -v180
	v_mul_f32_e32 v183, 0x3fb8aa3b, v183
	v_exp_f32_e32 v183, v183
	v_mul_f32_e32 v184, 0x3fb8aa3b, v184
	v_exp_f32_e32 v185, v184
	v_rcp_f32_e32 v184, v181
	v_add_f32_e32 v181, 1.0, v183
	v_rcp_f32_e32 v183, v181
	v_add_f32_e32 v181, 1.0, v185
	v_mul_f32_e64 v185, v96, -v180
	v_mul_f32_e32 v185, 0x3fb8aa3b, v185
	v_exp_f32_e32 v186, v185
	v_mul_f32_e64 v185, v92, -v180
	v_mul_f32_e32 v185, 0x3fb8aa3b, v185
	v_exp_f32_e32 v187, v185
	v_rcp_f32_e32 v185, v181
	v_add_f32_e32 v181, 1.0, v186
	v_rcp_f32_e32 v186, v181
	v_add_f32_e32 v181, 1.0, v187
	v_mul_f32_e64 v187, v97, -v180
	v_mul_f32_e32 v187, 0x3fb8aa3b, v187
	v_mul_f32_e64 v180, v93, -v180
	v_exp_f32_e32 v187, v187
	v_mul_f32_e32 v180, 0x3fb8aa3b, v180
	v_exp_f32_e32 v188, v180
	v_rcp_f32_e32 v180, v181
	v_add_f32_e32 v181, 1.0, v187
	v_rcp_f32_e32 v187, v181
	v_add_f32_e32 v181, 1.0, v188
	v_rcp_f32_e32 v181, v181
	v_lshlrev_b32_e32 v170, 16, v166
	v_and_b32_e32 v171, 0xffff0000, v166
	v_lshlrev_b32_e32 v166, 16, v167
	v_and_b32_e32 v167, 0xffff0000, v167
	v_lshlrev_b32_e32 v172, 16, v168
	v_and_b32_e32 v173, 0xffff0000, v168
	v_lshlrev_b32_e32 v168, 16, v169
	v_and_b32_e32 v169, 0xffff0000, v169
	v_lshlrev_b32_e32 v174, 16, v162
	v_and_b32_e32 v175, 0xffff0000, v162
	v_lshlrev_b32_e32 v162, 16, v163
	v_and_b32_e32 v163, 0xffff0000, v163
	v_lshlrev_b32_e32 v176, 16, v164
	v_and_b32_e32 v177, 0xffff0000, v164
	v_lshlrev_b32_e32 v164, 16, v165
	v_and_b32_e32 v165, 0xffff0000, v165
	v_pk_fma_f32 v[170:171], v[182:183], v[170:171], v[174:175]
	v_pk_fma_f32 v[172:173], v[184:185], v[172:173], v[176:177]
	v_pk_fma_f32 v[166:167], v[186:187], v[166:167], v[162:163]
	v_pk_fma_f32 v[168:169], v[180:181], v[168:169], v[164:165]
	s_mov_b64 s[12:13], -1
	s_and_b64 vcc, exec, s[8:9]
	v_cvt_pk_bf16_f32 v162, v170, v171
	v_cvt_pk_bf16_f32 v163, v166, v167
	v_cvt_pk_bf16_f32 v164, v172, v173
	v_cvt_pk_bf16_f32 v165, v168, v169
	s_cbranch_vccnz .LBB0_1159
	v_add_co_u32_e32 v166, vcc, 0x800000, v178
	s_mov_b64 s[12:13], 0
	s_nop 0
	v_addc_co_u32_e32 v167, vcc, 0, v179, vcc
	global_store_dwordx2 v[166:167], v[162:163], off nt
	global_store_dwordx2 v[166:167], v[164:165], off offset:512 nt

.LBB0_1161:
	s_nop 1
	v_fmamk_f32 v162, v207, 0x3a800000, v228
	v_mul_f32_e32 v163, 0x4b800000, v162
	v_cmp_gt_f32_e32 vcc, s69, v162
	v_lshlrev_b32_e32 v166, 16, v158
	v_and_b32_e32 v167, 0xffff0000, v158
	v_cndmask_b32_e32 v162, v162, v163, vcc
	v_rsq_f32_e32 v164, v162
	v_lshlrev_b32_e32 v158, 16, v159
	v_and_b32_e32 v159, 0xffff0000, v159
	v_lshlrev_b32_e32 v168, 16, v160
	v_mul_f32_e32 v165, 0x45800000, v164
	v_cndmask_b32_e32 v164, v164, v165, vcc
	v_mul_f32_e64 v165, v102, -v164
	v_mul_f32_e32 v165, 0x3fb8aa3b, v165
	v_mul_f32_e64 v174, v98, -v164
	v_exp_f32_e32 v165, v165
	v_mul_f32_e32 v174, 0x3fb8aa3b, v174
	v_exp_f32_e32 v175, v174
	v_mul_f32_e64 v176, v99, -v164
	v_add_f32_e32 v165, 1.0, v165
	v_rcp_f32_e32 v174, v165
	v_add_f32_e32 v165, 1.0, v175
	v_mul_f32_e64 v175, v103, -v164
	v_mul_f32_e32 v175, 0x3fb8aa3b, v175
	v_exp_f32_e32 v175, v175
	v_mul_f32_e32 v176, 0x3fb8aa3b, v176
	v_exp_f32_e32 v177, v176
	v_rcp_f32_e32 v176, v165
	v_add_f32_e32 v165, 1.0, v175
	v_rcp_f32_e32 v175, v165
	v_add_f32_e32 v165, 1.0, v177
	v_mul_f32_e64 v177, v104, -v164
	v_mul_f32_e32 v177, 0x3fb8aa3b, v177
	v_exp_f32_e32 v178, v177
	v_mul_f32_e64 v177, v100, -v164
	v_mul_f32_e32 v177, 0x3fb8aa3b, v177
	v_exp_f32_e32 v179, v177
	v_rcp_f32_e32 v177, v165
	v_add_f32_e32 v165, 1.0, v178
	v_rcp_f32_e32 v178, v165
	v_add_f32_e32 v165, 1.0, v179
	v_mul_f32_e64 v179, v105, -v164
	v_mul_f32_e32 v179, 0x3fb8aa3b, v179
	v_mul_f32_e64 v180, v101, -v164
	v_exp_f32_e32 v179, v179
	v_mul_f32_e32 v180, 0x3fb8aa3b, v180
	v_exp_f32_e32 v181, v180
	v_rcp_f32_e32 v180, v165
	v_add_f32_e32 v165, 1.0, v179
	v_rcp_f32_e32 v179, v165
	v_add_f32_e32 v165, 1.0, v181
	v_rcp_f32_e32 v181, v165
	v_and_b32_e32 v169, 0xffff0000, v160
	v_lshlrev_b32_e32 v160, 16, v161
	v_and_b32_e32 v161, 0xffff0000, v161
	v_lshlrev_b32_e32 v170, 16, v154
	v_and_b32_e32 v171, 0xffff0000, v154
	v_lshlrev_b32_e32 v154, 16, v155
	v_and_b32_e32 v155, 0xffff0000, v155
	v_lshlrev_b32_e32 v172, 16, v156
	v_and_b32_e32 v173, 0xffff0000, v156
	v_lshlrev_b32_e32 v156, 16, v157
	v_and_b32_e32 v157, 0xffff0000, v157
	v_pk_fma_f32 v[166:167], v[174:175], v[166:167], v[170:171]
	v_pk_fma_f32 v[168:169], v[176:177], v[168:169], v[172:173]
	v_pk_fma_f32 v[158:159], v[178:179], v[158:159], v[154:155]
	v_pk_fma_f32 v[160:161], v[180:181], v[160:161], v[156:157]
	v_lshl_add_u64 v[162:163], v[218:219], 0, s[38:39]
	v_cvt_pk_bf16_f32 v154, v166, v167
	v_cvt_pk_bf16_f32 v155, v158, v159
	s_mov_b64 s[12:13], -1
	s_and_b64 vcc, exec, s[8:9]
	v_cvt_pk_bf16_f32 v156, v168, v169
	v_cvt_pk_bf16_f32 v157, v160, v161
	s_cbranch_vccnz .LBB0_1163
	s_mov_b64 s[12:13], 0
	global_store_dwordx2 v[162:163], v[154:155], off nt
	global_store_dwordx2 v[162:163], v[156:157], off offset:512 nt

.LBB0_1165:
	v_mul_f32_e64 v165, v78, -v164
	v_mul_f32_e32 v165, 0x3fb8aa3b, v165
	v_mul_f32_e64 v166, v74, -v164
	v_exp_f32_e32 v165, v165
	v_mul_f32_e32 v166, 0x3fb8aa3b, v166
	v_exp_f32_e32 v167, v166
	v_mul_f32_e64 v168, v75, -v164
	v_add_f32_e32 v165, 1.0, v165
	v_rcp_f32_e32 v166, v165
	v_add_f32_e32 v165, 1.0, v167
	v_mul_f32_e64 v167, v79, -v164
	v_mul_f32_e32 v167, 0x3fb8aa3b, v167
	v_exp_f32_e32 v167, v167
	v_mul_f32_e32 v168, 0x3fb8aa3b, v168
	v_exp_f32_e32 v169, v168
	v_rcp_f32_e32 v168, v165
	v_add_f32_e32 v165, 1.0, v167
	v_rcp_f32_e32 v167, v165
	v_add_f32_e32 v165, 1.0, v169
	v_mul_f32_e64 v169, v80, -v164
	v_mul_f32_e32 v169, 0x3fb8aa3b, v169
	v_exp_f32_e32 v170, v169
	v_mul_f32_e64 v169, v76, -v164
	v_mul_f32_e32 v169, 0x3fb8aa3b, v169
	v_exp_f32_e32 v171, v169
	v_rcp_f32_e32 v169, v165
	v_add_f32_e32 v165, 1.0, v170
	v_rcp_f32_e32 v170, v165
	v_add_f32_e32 v165, 1.0, v171
	v_mul_f32_e64 v171, v81, -v164
	v_mul_f32_e32 v171, 0x3fb8aa3b, v171
	v_mul_f32_e64 v164, v77, -v164
	v_exp_f32_e32 v171, v171
	v_mul_f32_e32 v164, 0x3fb8aa3b, v164
	v_exp_f32_e32 v172, v164
	v_rcp_f32_e32 v164, v165
	v_add_f32_e32 v165, 1.0, v171
	v_rcp_f32_e32 v171, v165
	v_add_f32_e32 v165, 1.0, v172
	v_rcp_f32_e32 v165, v165
	v_lshlrev_b32_e32 v154, 16, v150
	v_and_b32_e32 v155, 0xffff0000, v150
	v_lshlrev_b32_e32 v150, 16, v151
	v_and_b32_e32 v151, 0xffff0000, v151
	v_lshlrev_b32_e32 v156, 16, v152
	v_and_b32_e32 v157, 0xffff0000, v152
	v_lshlrev_b32_e32 v152, 16, v153
	v_and_b32_e32 v153, 0xffff0000, v153
	v_lshlrev_b32_e32 v158, 16, v146
	v_and_b32_e32 v159, 0xffff0000, v146
	v_lshlrev_b32_e32 v146, 16, v147
	v_and_b32_e32 v147, 0xffff0000, v147
	v_lshlrev_b32_e32 v160, 16, v148
	v_and_b32_e32 v161, 0xffff0000, v148
	v_lshlrev_b32_e32 v148, 16, v149
	v_and_b32_e32 v149, 0xffff0000, v149
	v_pk_fma_f32 v[154:155], v[166:167], v[154:155], v[158:159]
	v_pk_fma_f32 v[156:157], v[168:169], v[156:157], v[160:161]
	v_pk_fma_f32 v[150:151], v[170:171], v[150:151], v[146:147]
	v_pk_fma_f32 v[152:153], v[164:165], v[152:153], v[148:149]
	s_mov_b64 s[12:13], -1
	s_and_b64 vcc, exec, s[8:9]
	v_cvt_pk_bf16_f32 v146, v154, v155
	v_cvt_pk_bf16_f32 v147, v150, v151
	v_cvt_pk_bf16_f32 v148, v156, v157
	v_cvt_pk_bf16_f32 v149, v152, v153
	s_cbranch_vccnz .LBB0_1167
	v_add_co_u32_e32 v150, vcc, 0x800000, v162
	s_mov_b64 s[12:13], 0
	s_nop 0
	v_addc_co_u32_e32 v151, vcc, 0, v163, vcc
	global_store_dwordx2 v[150:151], v[146:147], off nt
	global_store_dwordx2 v[150:151], v[148:149], off offset:512 nt

.LBB0_1169:
	s_nop 1
	v_fmamk_f32 v146, v205, 0x3a800000, v228
	v_mul_f32_e32 v147, 0x4b800000, v146
	v_cmp_gt_f32_e32 vcc, s69, v146
	s_lshl_b64 s[12:13], s[36:37], 1
	s_add_u32 s12, s43, s12
	v_cndmask_b32_e32 v146, v146, v147, vcc
	v_rsq_f32_e32 v146, v146
	s_addc_u32 s13, s41, s13
	v_lshlrev_b32_e32 v150, 16, v142
	v_and_b32_e32 v151, 0xffff0000, v142
	v_mul_f32_e32 v147, 0x45800000, v146
	v_cndmask_b32_e32 v148, v146, v147, vcc
	v_mul_f32_e64 v149, v86, -v148
	v_mul_f32_e32 v149, 0x3fb8aa3b, v149
	v_mul_f32_e64 v158, v82, -v148
	v_exp_f32_e32 v149, v149
	v_mul_f32_e32 v158, 0x3fb8aa3b, v158
	v_exp_f32_e32 v159, v158
	v_mul_f32_e64 v160, v83, -v148
	v_add_f32_e32 v149, 1.0, v149
	v_rcp_f32_e32 v158, v149
	v_add_f32_e32 v149, 1.0, v159
	v_mul_f32_e64 v159, v87, -v148
	v_mul_f32_e32 v159, 0x3fb8aa3b, v159
	v_exp_f32_e32 v159, v159
	v_mul_f32_e32 v160, 0x3fb8aa3b, v160
	v_exp_f32_e32 v161, v160
	v_rcp_f32_e32 v160, v149
	v_add_f32_e32 v149, 1.0, v159
	v_rcp_f32_e32 v159, v149
	v_add_f32_e32 v149, 1.0, v161
	v_mul_f32_e64 v161, v88, -v148
	v_mul_f32_e32 v161, 0x3fb8aa3b, v161
	v_exp_f32_e32 v162, v161
	v_mul_f32_e64 v161, v84, -v148
	v_mul_f32_e32 v161, 0x3fb8aa3b, v161
	v_exp_f32_e32 v163, v161
	v_rcp_f32_e32 v161, v149
	v_add_f32_e32 v149, 1.0, v162
	v_rcp_f32_e32 v162, v149
	v_add_f32_e32 v149, 1.0, v163
	v_mul_f32_e64 v163, v89, -v148
	v_mul_f32_e32 v163, 0x3fb8aa3b, v163
	v_mul_f32_e64 v164, v85, -v148
	v_exp_f32_e32 v163, v163
	v_mul_f32_e32 v164, 0x3fb8aa3b, v164
	v_exp_f32_e32 v165, v164
	v_rcp_f32_e32 v164, v149
	v_add_f32_e32 v149, 1.0, v163
	v_rcp_f32_e32 v163, v149
	v_add_f32_e32 v149, 1.0, v165
	v_rcp_f32_e32 v165, v149
	v_lshlrev_b32_e32 v142, 16, v143
	v_and_b32_e32 v143, 0xffff0000, v143
	v_lshlrev_b32_e32 v152, 16, v144
	v_and_b32_e32 v153, 0xffff0000, v144
	v_lshlrev_b32_e32 v144, 16, v145
	v_and_b32_e32 v145, 0xffff0000, v145
	v_lshlrev_b32_e32 v154, 16, v138
	v_and_b32_e32 v155, 0xffff0000, v138
	v_lshlrev_b32_e32 v138, 16, v139
	v_and_b32_e32 v139, 0xffff0000, v139
	v_lshlrev_b32_e32 v156, 16, v140
	v_and_b32_e32 v157, 0xffff0000, v140
	v_lshlrev_b32_e32 v140, 16, v141
	v_and_b32_e32 v141, 0xffff0000, v141
	v_lshl_add_u64 v[146:147], v[200:201], 1, s[12:13]
	v_pk_fma_f32 v[150:151], v[158:159], v[150:151], v[154:155]
	v_pk_fma_f32 v[152:153], v[160:161], v[152:153], v[156:157]
	v_pk_fma_f32 v[142:143], v[162:163], v[142:143], v[138:139]
	v_pk_fma_f32 v[144:145], v[164:165], v[144:145], v[140:141]
	v_lshl_add_u64 v[146:147], v[202:203], 1, v[146:147]
	v_cvt_pk_bf16_f32 v138, v150, v151
	v_cvt_pk_bf16_f32 v139, v142, v143
	s_mov_b64 s[12:13], -1
	s_and_b64 vcc, exec, s[8:9]
	v_cvt_pk_bf16_f32 v140, v152, v153
	v_cvt_pk_bf16_f32 v141, v144, v145
	s_cbranch_vccnz .LBB0_1171
	s_mov_b64 s[12:13], 0
	global_store_dwordx2 v[146:147], v[138:139], off nt
	global_store_dwordx2 v[146:147], v[140:141], off offset:512 nt

.LBB0_1173:
	v_mul_f32_e64 v149, v70, -v148
	v_mul_f32_e32 v149, 0x3fb8aa3b, v149
	v_mul_f32_e64 v150, v66, -v148
	v_exp_f32_e32 v149, v149
	v_mul_f32_e32 v150, 0x3fb8aa3b, v150
	v_exp_f32_e32 v151, v150
	v_mul_f32_e64 v152, v67, -v148
	v_add_f32_e32 v149, 1.0, v149
	v_rcp_f32_e32 v150, v149
	v_add_f32_e32 v149, 1.0, v151
	v_mul_f32_e64 v151, v71, -v148
	v_mul_f32_e32 v151, 0x3fb8aa3b, v151
	v_exp_f32_e32 v151, v151
	v_mul_f32_e32 v152, 0x3fb8aa3b, v152
	v_exp_f32_e32 v153, v152
	v_rcp_f32_e32 v152, v149
	v_add_f32_e32 v149, 1.0, v151
	v_rcp_f32_e32 v151, v149
	v_add_f32_e32 v149, 1.0, v153
	v_mul_f32_e64 v153, v72, -v148
	v_mul_f32_e32 v153, 0x3fb8aa3b, v153
	v_exp_f32_e32 v154, v153
	v_mul_f32_e64 v153, v68, -v148
	v_mul_f32_e32 v153, 0x3fb8aa3b, v153
	v_exp_f32_e32 v155, v153
	v_rcp_f32_e32 v153, v149
	v_add_f32_e32 v149, 1.0, v154
	v_rcp_f32_e32 v154, v149
	v_add_f32_e32 v149, 1.0, v155
	v_mul_f32_e64 v155, v73, -v148
	v_mul_f32_e32 v155, 0x3fb8aa3b, v155
	v_mul_f32_e64 v148, v69, -v148
	v_exp_f32_e32 v155, v155
	v_mul_f32_e32 v148, 0x3fb8aa3b, v148
	v_exp_f32_e32 v156, v148
	v_rcp_f32_e32 v148, v149
	v_add_f32_e32 v149, 1.0, v155
	v_rcp_f32_e32 v155, v149
	v_add_f32_e32 v149, 1.0, v156
	v_rcp_f32_e32 v149, v149
	v_lshlrev_b32_e32 v138, 16, v134
	v_and_b32_e32 v139, 0xffff0000, v134
	v_lshlrev_b32_e32 v134, 16, v135
	v_and_b32_e32 v135, 0xffff0000, v135
	v_lshlrev_b32_e32 v140, 16, v136
	v_and_b32_e32 v141, 0xffff0000, v136
	v_lshlrev_b32_e32 v136, 16, v137
	v_and_b32_e32 v137, 0xffff0000, v137
	v_lshlrev_b32_e32 v142, 16, v130
	v_and_b32_e32 v143, 0xffff0000, v130
	v_lshlrev_b32_e32 v130, 16, v131
	v_and_b32_e32 v131, 0xffff0000, v131
	v_lshlrev_b32_e32 v144, 16, v132
	v_and_b32_e32 v145, 0xffff0000, v132
	v_lshlrev_b32_e32 v132, 16, v133
	v_and_b32_e32 v133, 0xffff0000, v133
	v_pk_fma_f32 v[138:139], v[150:151], v[138:139], v[142:143]
	v_pk_fma_f32 v[140:141], v[152:153], v[140:141], v[144:145]
	v_pk_fma_f32 v[134:135], v[154:155], v[134:135], v[130:131]
	v_pk_fma_f32 v[136:137], v[148:149], v[136:137], v[132:133]
	s_mov_b64 s[12:13], -1
	s_and_b64 vcc, exec, s[8:9]
	v_cvt_pk_bf16_f32 v130, v138, v139
	v_cvt_pk_bf16_f32 v131, v134, v135
	v_cvt_pk_bf16_f32 v132, v140, v141
	v_cvt_pk_bf16_f32 v133, v136, v137
	s_cbranch_vccnz .LBB0_1175
	v_add_co_u32_e32 v134, vcc, 0x800000, v146
	s_mov_b64 s[12:13], 0
	s_nop 0
	v_addc_co_u32_e32 v135, vcc, 0, v147, vcc
	global_store_dwordx2 v[134:135], v[130:131], off nt
	global_store_dwordx2 v[134:135], v[132:133], off offset:512 nt

.LBB0_1197:
	s_waitcnt vmcnt(0)
	v_fmamk_f32 v142, v142, 0x3a800000, v228
	v_mul_f32_e32 v143, 0x4b800000, v142
	v_cmp_gt_f32_e32 vcc, s69, v142
	s_lshl_b32 s8, s50, 2
	s_or_b32 s8, s8, s64
	v_cndmask_b32_e32 v142, v142, v143, vcc
	v_rsq_f32_e32 v142, v142
	s_lshl_b32 s12, s48, 1
	s_ashr_i32 s9, s8, 31
	s_or_b32 s12, s12, 1
	v_mul_f32_e32 v143, 0x45800000, v142
	v_cndmask_b32_e32 v151, v142, v143, vcc
	v_mul_f32_e64 v162, v63, -v151
	v_mul_f32_e64 v161, v58, -v151
	v_mul_f32_e32 v162, 0x3fb8aa3b, v162
	v_mul_f32_e32 v161, 0x3fb8aa3b, v161
	v_exp_f32_e32 v163, v162
	v_mul_f32_e64 v162, v59, -v151
	v_exp_f32_e32 v161, v161
	v_mul_f32_e32 v162, 0x3fb8aa3b, v162
	v_exp_f32_e32 v164, v162
	v_mul_f32_e64 v166, v65, -v151
	v_add_f32_e32 v161, 1.0, v161
	v_mul_f32_e64 v165, v60, -v151
	v_mul_f32_e32 v166, 0x3fb8aa3b, v166
	v_mul_f32_e64 v160, v62, -v151
	v_rcp_f32_e32 v162, v161
	v_add_f32_e32 v161, 1.0, v163
	v_add_f32_e32 v163, 1.0, v164
	v_mul_f32_e64 v164, v64, -v151
	v_mul_f32_e32 v165, 0x3fb8aa3b, v165
	v_exp_f32_e32 v167, v166
	v_mul_f32_e64 v166, v61, -v151
	v_mul_f32_e32 v160, 0x3fb8aa3b, v160
	v_mul_f32_e32 v164, 0x3fb8aa3b, v164
	v_exp_f32_e32 v165, v165
	v_mul_f32_e32 v166, 0x3fb8aa3b, v166
	v_exp_f32_e32 v160, v160
	v_exp_f32_e32 v164, v164
	v_exp_f32_e32 v168, v166
	s_ashr_i32 s13, s12, 31
	s_lshl_b64 s[8:9], s[8:9], 22
	s_add_u32 s34, s56, s8
	v_add_f32_e32 v165, 1.0, v165
	s_addc_u32 s35, s57, s9
	s_lshl_b64 s[8:9], s[12:13], 14
	v_add_f32_e32 v160, 1.0, v160
	v_add_f32_e32 v164, 1.0, v164
	v_rcp_f32_e32 v166, v165
	v_add_f32_e32 v165, 1.0, v167
	v_add_f32_e32 v167, 1.0, v168
	s_add_u32 s43, s34, s8
	v_rcp_f32_e32 v160, v160
	v_rcp_f32_e32 v161, v161
	v_rcp_f32_e32 v163, v163
	v_rcp_f32_e32 v164, v164
	v_rcp_f32_e32 v165, v165
	v_rcp_f32_e32 v167, v167
	s_addc_u32 s41, s35, s9
	s_lshl_b64 s[8:9], s[28:29], 1
	s_add_u32 s8, s43, s8
	s_addc_u32 s9, s41, s9
	v_lshlrev_b32_e32 v152, 16, v126
	v_and_b32_e32 v153, 0xffff0000, v126
	v_lshlrev_b32_e32 v126, 16, v127
	v_and_b32_e32 v127, 0xffff0000, v127
	v_lshlrev_b32_e32 v154, 16, v128
	v_and_b32_e32 v155, 0xffff0000, v128
	v_lshlrev_b32_e32 v128, 16, v129
	v_and_b32_e32 v129, 0xffff0000, v129
	v_lshlrev_b32_e32 v156, 16, v122
	v_and_b32_e32 v157, 0xffff0000, v122
	v_lshlrev_b32_e32 v122, 16, v123
	v_and_b32_e32 v123, 0xffff0000, v123
	v_lshlrev_b32_e32 v158, 16, v124
	v_and_b32_e32 v159, 0xffff0000, v124
	v_lshlrev_b32_e32 v124, 16, v125
	v_and_b32_e32 v125, 0xffff0000, v125
	v_lshl_add_u64 v[142:143], v[200:201], 1, s[8:9]
	v_pk_fma_f32 v[152:153], v[160:161], v[152:153], v[156:157]
	v_pk_fma_f32 v[154:155], v[162:163], v[154:155], v[158:159]
	v_pk_fma_f32 v[126:127], v[164:165], v[126:127], v[122:123]
	v_pk_fma_f32 v[128:129], v[166:167], v[128:129], v[124:125]
	s_cmp_gt_i32 s72, 1
	v_lshl_add_u64 v[142:143], v[202:203], 1, v[142:143]
	s_cselect_b64 s[12:13], -1, 0
	s_cmp_lt_i32 s72, 2
	v_cvt_pk_bf16_f32 v122, v152, v153
	v_cvt_pk_bf16_f32 v123, v126, v127
	s_mov_b64 s[8:9], -1
	v_cvt_pk_bf16_f32 v124, v154, v155
	v_cvt_pk_bf16_f32 v125, v128, v129
	s_cbranch_scc1 .LBB0_1199
	s_mov_b64 s[8:9], 0
	global_store_dwordx2 v[142:143], v[122:123], off nt
	global_store_dwordx2 v[142:143], v[124:125], off offset:512 nt

.LBB0_1201:
	v_mul_f32_e64 v152, v47, -v151
	v_mul_f32_e64 v147, v42, -v151
	v_mul_f32_e32 v152, 0x3fb8aa3b, v152
	v_mul_f32_e32 v147, 0x3fb8aa3b, v147
	v_exp_f32_e32 v153, v152
	v_mul_f32_e64 v152, v43, -v151
	v_exp_f32_e32 v147, v147
	v_mul_f32_e32 v152, 0x3fb8aa3b, v152
	v_exp_f32_e32 v154, v152
	v_mul_f32_e64 v155, v44, -v151
	v_add_f32_e32 v147, 1.0, v147
	v_mul_f32_e64 v146, v46, -v151
	v_rcp_f32_e32 v152, v147
	v_add_f32_e32 v147, 1.0, v153
	v_add_f32_e32 v153, 1.0, v154
	v_mul_f32_e64 v154, v48, -v151
	v_mul_f32_e32 v155, 0x3fb8aa3b, v155
	v_mul_f32_e64 v156, v49, -v151
	v_mul_f32_e64 v151, v45, -v151
	v_mul_f32_e32 v146, 0x3fb8aa3b, v146
	v_mul_f32_e32 v154, 0x3fb8aa3b, v154
	v_exp_f32_e32 v155, v155
	v_mul_f32_e32 v156, 0x3fb8aa3b, v156
	v_mul_f32_e32 v151, 0x3fb8aa3b, v151
	v_exp_f32_e32 v146, v146
	v_exp_f32_e32 v154, v154
	v_exp_f32_e32 v157, v156
	v_exp_f32_e32 v151, v151
	v_add_f32_e32 v155, 1.0, v155
	v_add_f32_e32 v146, 1.0, v146
	v_add_f32_e32 v154, 1.0, v154
	v_rcp_f32_e32 v156, v155
	v_add_f32_e32 v155, 1.0, v157
	v_add_f32_e32 v151, 1.0, v151
	v_rcp_f32_e32 v146, v146
	v_rcp_f32_e32 v147, v147
	v_rcp_f32_e32 v153, v153
	v_rcp_f32_e32 v154, v154
	v_rcp_f32_e32 v155, v155
	v_rcp_f32_e32 v157, v151
	v_lshlrev_b32_e32 v122, 16, v118
	v_and_b32_e32 v123, 0xffff0000, v118
	v_lshlrev_b32_e32 v118, 16, v119
	v_and_b32_e32 v119, 0xffff0000, v119
	v_lshlrev_b32_e32 v124, 16, v120
	v_and_b32_e32 v125, 0xffff0000, v120
	v_lshlrev_b32_e32 v120, 16, v121
	v_and_b32_e32 v121, 0xffff0000, v121
	v_lshlrev_b32_e32 v126, 16, v114
	v_and_b32_e32 v127, 0xffff0000, v114
	v_lshlrev_b32_e32 v114, 16, v115
	v_and_b32_e32 v115, 0xffff0000, v115
	v_lshlrev_b32_e32 v128, 16, v116
	v_and_b32_e32 v129, 0xffff0000, v116
	v_lshlrev_b32_e32 v116, 16, v117
	v_and_b32_e32 v117, 0xffff0000, v117
	v_pk_fma_f32 v[122:123], v[146:147], v[122:123], v[126:127]
	v_pk_fma_f32 v[124:125], v[152:153], v[124:125], v[128:129]
	v_pk_fma_f32 v[118:119], v[154:155], v[118:119], v[114:115]
	v_pk_fma_f32 v[120:121], v[156:157], v[120:121], v[116:117]
	v_cndmask_b32_e64 v114, 0, 1, s[12:13]
	s_mov_b64 s[34:35], -1
	v_cmp_ne_u32_e64 s[8:9], 1, v114
	s_andn2_b64 vcc, exec, s[12:13]
	v_cvt_pk_bf16_f32 v114, v122, v123
	v_cvt_pk_bf16_f32 v115, v118, v119
	v_cvt_pk_bf16_f32 v116, v124, v125
	v_cvt_pk_bf16_f32 v117, v120, v121
	s_cbranch_vccnz .LBB0_1203
	v_add_co_u32_e32 v118, vcc, 0x800000, v142
	s_mov_b64 s[34:35], 0
	s_nop 0
	v_addc_co_u32_e32 v119, vcc, 0, v143, vcc
	global_store_dwordx2 v[118:119], v[114:115], off nt
	global_store_dwordx2 v[118:119], v[116:117], off offset:512 nt

.LBB0_1205:
	s_nop 1
	v_fmamk_f32 v114, v150, 0x3a800000, v228
	v_mul_f32_e32 v115, 0x4b800000, v114
	v_cmp_gt_f32_e32 vcc, s69, v114
	s_lshl_b64 s[12:13], s[30:31], 1
	s_add_u32 s12, s43, s12
	v_cndmask_b32_e32 v114, v114, v115, vcc
	v_rsq_f32_e32 v114, v114
	s_addc_u32 s13, s41, s13
	v_lshlrev_b32_e32 v118, 16, v110
	v_and_b32_e32 v119, 0xffff0000, v110
	v_mul_f32_e32 v115, 0x45800000, v114
	v_cndmask_b32_e32 v116, v114, v115, vcc
	v_mul_f32_e64 v117, v54, -v116
	v_mul_f32_e32 v117, 0x3fb8aa3b, v117
	v_mul_f32_e64 v126, v50, -v116
	v_exp_f32_e32 v117, v117
	v_mul_f32_e32 v126, 0x3fb8aa3b, v126
	v_exp_f32_e32 v127, v126
	v_mul_f32_e64 v128, v51, -v116
	v_add_f32_e32 v117, 1.0, v117
	v_rcp_f32_e32 v126, v117
	v_add_f32_e32 v117, 1.0, v127
	v_mul_f32_e64 v127, v55, -v116
	v_mul_f32_e32 v127, 0x3fb8aa3b, v127
	v_exp_f32_e32 v127, v127
	v_mul_f32_e32 v128, 0x3fb8aa3b, v128
	v_exp_f32_e32 v129, v128
	v_rcp_f32_e32 v128, v117
	v_add_f32_e32 v117, 1.0, v127
	v_rcp_f32_e32 v127, v117
	v_add_f32_e32 v117, 1.0, v129
	v_mul_f32_e64 v129, v56, -v116
	v_mul_f32_e32 v129, 0x3fb8aa3b, v129
	v_exp_f32_e32 v144, v129
	v_mul_f32_e64 v129, v52, -v116
	v_mul_f32_e32 v129, 0x3fb8aa3b, v129
	v_exp_f32_e32 v145, v129
	v_rcp_f32_e32 v129, v117
	v_add_f32_e32 v117, 1.0, v144
	v_rcp_f32_e32 v144, v117
	v_add_f32_e32 v117, 1.0, v145
	v_mul_f32_e64 v145, v57, -v116
	v_mul_f32_e32 v145, 0x3fb8aa3b, v145
	v_mul_f32_e64 v146, v53, -v116
	v_exp_f32_e32 v145, v145
	v_mul_f32_e32 v146, 0x3fb8aa3b, v146
	v_exp_f32_e32 v147, v146
	v_rcp_f32_e32 v146, v117
	v_add_f32_e32 v117, 1.0, v145
	v_rcp_f32_e32 v145, v117
	v_add_f32_e32 v117, 1.0, v147
	v_rcp_f32_e32 v147, v117
	v_lshlrev_b32_e32 v110, 16, v111
	v_and_b32_e32 v111, 0xffff0000, v111
	v_lshlrev_b32_e32 v120, 16, v112
	v_and_b32_e32 v121, 0xffff0000, v112
	v_lshlrev_b32_e32 v112, 16, v113
	v_and_b32_e32 v113, 0xffff0000, v113
	v_lshlrev_b32_e32 v122, 16, v106
	v_and_b32_e32 v123, 0xffff0000, v106
	v_lshlrev_b32_e32 v106, 16, v107
	v_and_b32_e32 v107, 0xffff0000, v107
	v_lshlrev_b32_e32 v124, 16, v108
	v_and_b32_e32 v125, 0xffff0000, v108
	v_lshlrev_b32_e32 v108, 16, v109
	v_and_b32_e32 v109, 0xffff0000, v109
	v_lshl_add_u64 v[114:115], v[200:201], 1, s[12:13]
	v_pk_fma_f32 v[118:119], v[126:127], v[118:119], v[122:123]
	v_pk_fma_f32 v[120:121], v[128:129], v[120:121], v[124:125]
	v_pk_fma_f32 v[110:111], v[144:145], v[110:111], v[106:107]
	v_pk_fma_f32 v[112:113], v[146:147], v[112:113], v[108:109]
	v_lshl_add_u64 v[114:115], v[202:203], 1, v[114:115]
	v_cvt_pk_bf16_f32 v106, v118, v119
	v_cvt_pk_bf16_f32 v107, v110, v111
	s_mov_b64 s[12:13], -1
	s_and_b64 vcc, exec, s[8:9]
	v_cvt_pk_bf16_f32 v108, v120, v121
	v_cvt_pk_bf16_f32 v109, v112, v113
	s_cbranch_vccnz .LBB0_1207
	s_mov_b64 s[12:13], 0
	global_store_dwordx2 v[114:115], v[106:107], off nt
	global_store_dwordx2 v[114:115], v[108:109], off offset:512 nt

.LBB0_1209:
	v_mul_f32_e64 v117, v30, -v116
	v_mul_f32_e32 v117, 0x3fb8aa3b, v117
	v_mul_f32_e64 v118, v26, -v116
	v_exp_f32_e32 v117, v117
	v_mul_f32_e32 v118, 0x3fb8aa3b, v118
	v_exp_f32_e32 v119, v118
	v_mul_f32_e64 v120, v27, -v116
	v_add_f32_e32 v117, 1.0, v117
	v_rcp_f32_e32 v118, v117
	v_add_f32_e32 v117, 1.0, v119
	v_mul_f32_e64 v119, v31, -v116
	v_mul_f32_e32 v119, 0x3fb8aa3b, v119
	v_exp_f32_e32 v119, v119
	v_mul_f32_e32 v120, 0x3fb8aa3b, v120
	v_exp_f32_e32 v121, v120
	v_rcp_f32_e32 v120, v117
	v_add_f32_e32 v117, 1.0, v119
	v_rcp_f32_e32 v119, v117
	v_add_f32_e32 v117, 1.0, v121
	v_mul_f32_e64 v121, v32, -v116
	v_mul_f32_e32 v121, 0x3fb8aa3b, v121
	v_exp_f32_e32 v122, v121
	v_mul_f32_e64 v121, v28, -v116
	v_mul_f32_e32 v121, 0x3fb8aa3b, v121
	v_exp_f32_e32 v123, v121
	v_rcp_f32_e32 v121, v117
	v_add_f32_e32 v117, 1.0, v122
	v_rcp_f32_e32 v122, v117
	v_add_f32_e32 v117, 1.0, v123
	v_mul_f32_e64 v123, v33, -v116
	v_mul_f32_e32 v123, 0x3fb8aa3b, v123
	v_mul_f32_e64 v116, v29, -v116
	v_exp_f32_e32 v123, v123
	v_mul_f32_e32 v116, 0x3fb8aa3b, v116
	v_exp_f32_e32 v124, v116
	v_rcp_f32_e32 v116, v117
	v_add_f32_e32 v117, 1.0, v123
	v_rcp_f32_e32 v123, v117
	v_add_f32_e32 v117, 1.0, v124
	v_rcp_f32_e32 v117, v117
	v_lshlrev_b32_e32 v106, 16, v102
	v_and_b32_e32 v107, 0xffff0000, v102
	v_lshlrev_b32_e32 v102, 16, v103
	v_and_b32_e32 v103, 0xffff0000, v103
	v_lshlrev_b32_e32 v108, 16, v104
	v_and_b32_e32 v109, 0xffff0000, v104
	v_lshlrev_b32_e32 v104, 16, v105
	v_and_b32_e32 v105, 0xffff0000, v105
	v_lshlrev_b32_e32 v110, 16, v98
	v_and_b32_e32 v111, 0xffff0000, v98
	v_lshlrev_b32_e32 v98, 16, v99
	v_and_b32_e32 v99, 0xffff0000, v99
	v_lshlrev_b32_e32 v112, 16, v100
	v_and_b32_e32 v113, 0xffff0000, v100
	v_lshlrev_b32_e32 v100, 16, v101
	v_and_b32_e32 v101, 0xffff0000, v101
	v_pk_fma_f32 v[106:107], v[118:119], v[106:107], v[110:111]
	v_pk_fma_f32 v[108:109], v[120:121], v[108:109], v[112:113]
	v_pk_fma_f32 v[102:103], v[122:123], v[102:103], v[98:99]
	v_pk_fma_f32 v[104:105], v[116:117], v[104:105], v[100:101]
	s_mov_b64 s[12:13], -1
	s_and_b64 vcc, exec, s[8:9]
	v_cvt_pk_bf16_f32 v98, v106, v107
	v_cvt_pk_bf16_f32 v99, v102, v103
	v_cvt_pk_bf16_f32 v100, v108, v109
	v_cvt_pk_bf16_f32 v101, v104, v105
	s_cbranch_vccnz .LBB0_1211
	v_add_co_u32_e32 v102, vcc, 0x800000, v114
	s_mov_b64 s[12:13], 0
	s_nop 0
	v_addc_co_u32_e32 v103, vcc, 0, v115, vcc
	global_store_dwordx2 v[102:103], v[98:99], off nt
	global_store_dwordx2 v[102:103], v[100:101], off offset:512 nt

.LBB0_1213:
	s_nop 1
	v_fmamk_f32 v98, v149, 0x3a800000, v228
	v_mul_f32_e32 v99, 0x4b800000, v98
	v_cmp_gt_f32_e32 vcc, s69, v98
	v_lshlrev_b32_e32 v102, 16, v94
	v_and_b32_e32 v103, 0xffff0000, v94
	v_cndmask_b32_e32 v98, v98, v99, vcc
	v_rsq_f32_e32 v100, v98
	v_lshlrev_b32_e32 v94, 16, v95
	v_and_b32_e32 v95, 0xffff0000, v95
	v_lshlrev_b32_e32 v104, 16, v96
	v_mul_f32_e32 v101, 0x45800000, v100
	v_cndmask_b32_e32 v100, v100, v101, vcc
	v_mul_f32_e64 v101, v38, -v100
	v_mul_f32_e32 v101, 0x3fb8aa3b, v101
	v_mul_f32_e64 v110, v34, -v100
	v_exp_f32_e32 v101, v101
	v_mul_f32_e32 v110, 0x3fb8aa3b, v110
	v_exp_f32_e32 v111, v110
	v_mul_f32_e64 v112, v35, -v100
	v_add_f32_e32 v101, 1.0, v101
	v_rcp_f32_e32 v110, v101
	v_add_f32_e32 v101, 1.0, v111
	v_mul_f32_e64 v111, v39, -v100
	v_mul_f32_e32 v111, 0x3fb8aa3b, v111
	v_exp_f32_e32 v111, v111
	v_mul_f32_e32 v112, 0x3fb8aa3b, v112
	v_exp_f32_e32 v113, v112
	v_rcp_f32_e32 v112, v101
	v_add_f32_e32 v101, 1.0, v111
	v_rcp_f32_e32 v111, v101
	v_add_f32_e32 v101, 1.0, v113
	v_mul_f32_e64 v113, v40, -v100
	v_mul_f32_e32 v113, 0x3fb8aa3b, v113
	v_exp_f32_e32 v114, v113
	v_mul_f32_e64 v113, v36, -v100
	v_mul_f32_e32 v113, 0x3fb8aa3b, v113
	v_exp_f32_e32 v115, v113
	v_rcp_f32_e32 v113, v101
	v_add_f32_e32 v101, 1.0, v114
	v_rcp_f32_e32 v114, v101
	v_add_f32_e32 v101, 1.0, v115
	v_mul_f32_e64 v115, v41, -v100
	v_mul_f32_e32 v115, 0x3fb8aa3b, v115
	v_mul_f32_e64 v116, v37, -v100
	v_exp_f32_e32 v115, v115
	v_mul_f32_e32 v116, 0x3fb8aa3b, v116
	v_exp_f32_e32 v117, v116
	v_rcp_f32_e32 v116, v101
	v_add_f32_e32 v101, 1.0, v115
	v_rcp_f32_e32 v115, v101
	v_add_f32_e32 v101, 1.0, v117
	v_rcp_f32_e32 v117, v101
	v_and_b32_e32 v105, 0xffff0000, v96
	v_lshlrev_b32_e32 v96, 16, v97
	v_and_b32_e32 v97, 0xffff0000, v97
	v_lshlrev_b32_e32 v106, 16, v90
	v_and_b32_e32 v107, 0xffff0000, v90
	v_lshlrev_b32_e32 v90, 16, v91
	v_and_b32_e32 v91, 0xffff0000, v91
	v_lshlrev_b32_e32 v108, 16, v92
	v_and_b32_e32 v109, 0xffff0000, v92
	v_lshlrev_b32_e32 v92, 16, v93
	v_and_b32_e32 v93, 0xffff0000, v93
	v_pk_fma_f32 v[102:103], v[110:111], v[102:103], v[106:107]
	v_pk_fma_f32 v[104:105], v[112:113], v[104:105], v[108:109]
	v_pk_fma_f32 v[94:95], v[114:115], v[94:95], v[90:91]
	v_pk_fma_f32 v[96:97], v[116:117], v[96:97], v[92:93]
	v_lshl_add_u64 v[98:99], v[142:143], 0, s[38:39]
	v_cvt_pk_bf16_f32 v90, v102, v103
	v_cvt_pk_bf16_f32 v91, v94, v95
	s_mov_b64 s[12:13], -1
	s_and_b64 vcc, exec, s[8:9]
	v_cvt_pk_bf16_f32 v92, v104, v105
	v_cvt_pk_bf16_f32 v93, v96, v97
	s_cbranch_vccnz .LBB0_1215
	s_mov_b64 s[12:13], 0
	global_store_dwordx2 v[98:99], v[90:91], off nt
	global_store_dwordx2 v[98:99], v[92:93], off offset:512 nt

.LBB0_1217:
	v_mul_f32_e64 v101, v14, -v100
	v_mul_f32_e32 v101, 0x3fb8aa3b, v101
	v_mul_f32_e64 v102, v10, -v100
	v_exp_f32_e32 v101, v101
	v_mul_f32_e32 v102, 0x3fb8aa3b, v102
	v_exp_f32_e32 v103, v102
	v_mul_f32_e64 v104, v11, -v100
	v_add_f32_e32 v101, 1.0, v101
	v_rcp_f32_e32 v102, v101
	v_add_f32_e32 v101, 1.0, v103
	v_mul_f32_e64 v103, v15, -v100
	v_mul_f32_e32 v103, 0x3fb8aa3b, v103
	v_exp_f32_e32 v103, v103
	v_mul_f32_e32 v104, 0x3fb8aa3b, v104
	v_exp_f32_e32 v105, v104
	v_rcp_f32_e32 v104, v101
	v_add_f32_e32 v101, 1.0, v103
	v_rcp_f32_e32 v103, v101
	v_add_f32_e32 v101, 1.0, v105
	v_mul_f32_e64 v105, v16, -v100
	v_mul_f32_e32 v105, 0x3fb8aa3b, v105
	v_exp_f32_e32 v106, v105
	v_mul_f32_e64 v105, v12, -v100
	v_mul_f32_e32 v105, 0x3fb8aa3b, v105
	v_exp_f32_e32 v107, v105
	v_rcp_f32_e32 v105, v101
	v_add_f32_e32 v101, 1.0, v106
	v_rcp_f32_e32 v106, v101
	v_add_f32_e32 v101, 1.0, v107
	v_mul_f32_e64 v107, v17, -v100
	v_mul_f32_e32 v107, 0x3fb8aa3b, v107
	v_mul_f32_e64 v100, v13, -v100
	v_exp_f32_e32 v107, v107
	v_mul_f32_e32 v100, 0x3fb8aa3b, v100
	v_exp_f32_e32 v108, v100
	v_rcp_f32_e32 v100, v101
	v_add_f32_e32 v101, 1.0, v107
	v_rcp_f32_e32 v107, v101
	v_add_f32_e32 v101, 1.0, v108
	v_rcp_f32_e32 v101, v101
	v_lshlrev_b32_e32 v90, 16, v86
	v_and_b32_e32 v91, 0xffff0000, v86
	v_lshlrev_b32_e32 v86, 16, v87
	v_and_b32_e32 v87, 0xffff0000, v87
	v_lshlrev_b32_e32 v92, 16, v88
	v_and_b32_e32 v93, 0xffff0000, v88
	v_lshlrev_b32_e32 v88, 16, v89
	v_and_b32_e32 v89, 0xffff0000, v89
	v_lshlrev_b32_e32 v94, 16, v82
	v_and_b32_e32 v95, 0xffff0000, v82
	v_lshlrev_b32_e32 v82, 16, v83
	v_and_b32_e32 v83, 0xffff0000, v83
	v_lshlrev_b32_e32 v96, 16, v84
	v_and_b32_e32 v97, 0xffff0000, v84
	v_lshlrev_b32_e32 v84, 16, v85
	v_and_b32_e32 v85, 0xffff0000, v85
	v_pk_fma_f32 v[90:91], v[102:103], v[90:91], v[94:95]
	v_pk_fma_f32 v[92:93], v[104:105], v[92:93], v[96:97]
	v_pk_fma_f32 v[86:87], v[106:107], v[86:87], v[82:83]
	v_pk_fma_f32 v[88:89], v[100:101], v[88:89], v[84:85]
	s_mov_b64 s[12:13], -1
	s_and_b64 vcc, exec, s[8:9]
	v_cvt_pk_bf16_f32 v82, v90, v91
	v_cvt_pk_bf16_f32 v83, v86, v87
	v_cvt_pk_bf16_f32 v84, v92, v93
	v_cvt_pk_bf16_f32 v85, v88, v89
	s_cbranch_vccnz .LBB0_1219
	v_add_co_u32_e32 v86, vcc, 0x800000, v98
	s_mov_b64 s[12:13], 0
	s_nop 0
	v_addc_co_u32_e32 v87, vcc, 0, v99, vcc
	global_store_dwordx2 v[86:87], v[82:83], off nt
	global_store_dwordx2 v[86:87], v[84:85], off offset:512 nt

.LBB0_1221:
	s_nop 1
	v_fmamk_f32 v82, v148, 0x3a800000, v228
	v_mul_f32_e32 v83, 0x4b800000, v82
	v_cmp_gt_f32_e32 vcc, s69, v82
	s_lshl_b64 s[12:13], s[36:37], 1
	s_add_u32 s12, s43, s12
	v_cndmask_b32_e32 v82, v82, v83, vcc
	v_rsq_f32_e32 v82, v82
	s_addc_u32 s13, s41, s13
	v_lshlrev_b32_e32 v86, 16, v78
	v_and_b32_e32 v87, 0xffff0000, v78
	v_mul_f32_e32 v83, 0x45800000, v82
	v_cndmask_b32_e32 v84, v82, v83, vcc
	v_mul_f32_e64 v85, v22, -v84
	v_mul_f32_e32 v85, 0x3fb8aa3b, v85
	v_mul_f32_e64 v94, v18, -v84
	v_exp_f32_e32 v85, v85
	v_mul_f32_e32 v94, 0x3fb8aa3b, v94
	v_exp_f32_e32 v95, v94
	v_mul_f32_e64 v96, v19, -v84
	v_add_f32_e32 v85, 1.0, v85
	v_rcp_f32_e32 v94, v85
	v_add_f32_e32 v85, 1.0, v95
	v_mul_f32_e64 v95, v23, -v84
	v_mul_f32_e32 v95, 0x3fb8aa3b, v95
	v_exp_f32_e32 v95, v95
	v_mul_f32_e32 v96, 0x3fb8aa3b, v96
	v_exp_f32_e32 v97, v96
	v_rcp_f32_e32 v96, v85
	v_add_f32_e32 v85, 1.0, v95
	v_rcp_f32_e32 v95, v85
	v_add_f32_e32 v85, 1.0, v97
	v_mul_f32_e64 v97, v24, -v84
	v_mul_f32_e32 v97, 0x3fb8aa3b, v97
	v_exp_f32_e32 v98, v97
	v_mul_f32_e64 v97, v20, -v84
	v_mul_f32_e32 v97, 0x3fb8aa3b, v97
	v_exp_f32_e32 v99, v97
	v_rcp_f32_e32 v97, v85
	v_add_f32_e32 v85, 1.0, v98
	v_rcp_f32_e32 v98, v85
	v_add_f32_e32 v85, 1.0, v99
	v_mul_f32_e64 v99, v25, -v84
	v_mul_f32_e32 v99, 0x3fb8aa3b, v99
	v_mul_f32_e64 v100, v21, -v84
	v_exp_f32_e32 v99, v99
	v_mul_f32_e32 v100, 0x3fb8aa3b, v100
	v_exp_f32_e32 v101, v100
	v_rcp_f32_e32 v100, v85
	v_add_f32_e32 v85, 1.0, v99
	v_rcp_f32_e32 v99, v85
	v_add_f32_e32 v85, 1.0, v101
	v_rcp_f32_e32 v101, v85
	v_lshlrev_b32_e32 v78, 16, v79
	v_and_b32_e32 v79, 0xffff0000, v79
	v_lshlrev_b32_e32 v88, 16, v80
	v_and_b32_e32 v89, 0xffff0000, v80
	v_lshlrev_b32_e32 v80, 16, v81
	v_and_b32_e32 v81, 0xffff0000, v81
	v_lshlrev_b32_e32 v90, 16, v74
	v_and_b32_e32 v91, 0xffff0000, v74
	v_lshlrev_b32_e32 v74, 16, v75
	v_and_b32_e32 v75, 0xffff0000, v75
	v_lshlrev_b32_e32 v92, 16, v76
	v_and_b32_e32 v93, 0xffff0000, v76
	v_lshlrev_b32_e32 v76, 16, v77
	v_and_b32_e32 v77, 0xffff0000, v77
	v_lshl_add_u64 v[82:83], v[200:201], 1, s[12:13]
	v_pk_fma_f32 v[86:87], v[94:95], v[86:87], v[90:91]
	v_pk_fma_f32 v[88:89], v[96:97], v[88:89], v[92:93]
	v_pk_fma_f32 v[78:79], v[98:99], v[78:79], v[74:75]
	v_pk_fma_f32 v[80:81], v[100:101], v[80:81], v[76:77]
	v_lshl_add_u64 v[82:83], v[202:203], 1, v[82:83]
	v_cvt_pk_bf16_f32 v74, v86, v87
	v_cvt_pk_bf16_f32 v75, v78, v79
	s_mov_b64 s[12:13], -1
	s_and_b64 vcc, exec, s[8:9]
	v_cvt_pk_bf16_f32 v76, v88, v89
	v_cvt_pk_bf16_f32 v77, v80, v81
	s_cbranch_vccnz .LBB0_1223
	s_mov_b64 s[12:13], 0
	global_store_dwordx2 v[82:83], v[74:75], off nt
	global_store_dwordx2 v[82:83], v[76:77], off offset:512 nt

.LBB0_1225:
	v_mul_f32_e64 v85, v6, -v84
	v_mul_f32_e32 v85, 0x3fb8aa3b, v85
	v_mul_f32_e64 v86, v2, -v84
	v_exp_f32_e32 v85, v85
	v_mul_f32_e32 v86, 0x3fb8aa3b, v86
	v_exp_f32_e32 v87, v86
	v_mul_f32_e64 v88, v3, -v84
	v_add_f32_e32 v85, 1.0, v85
	v_rcp_f32_e32 v86, v85
	v_add_f32_e32 v85, 1.0, v87
	v_mul_f32_e64 v87, v7, -v84
	v_mul_f32_e32 v87, 0x3fb8aa3b, v87
	v_exp_f32_e32 v87, v87
	v_mul_f32_e32 v88, 0x3fb8aa3b, v88
	v_exp_f32_e32 v89, v88
	v_rcp_f32_e32 v88, v85
	v_add_f32_e32 v85, 1.0, v87
	v_rcp_f32_e32 v87, v85
	v_add_f32_e32 v85, 1.0, v89
	v_mul_f32_e64 v89, v8, -v84
	v_mul_f32_e32 v89, 0x3fb8aa3b, v89
	v_exp_f32_e32 v90, v89
	v_mul_f32_e64 v89, v4, -v84
	v_mul_f32_e32 v89, 0x3fb8aa3b, v89
	v_exp_f32_e32 v91, v89
	v_rcp_f32_e32 v89, v85
	v_add_f32_e32 v85, 1.0, v90
	v_rcp_f32_e32 v90, v85
	v_add_f32_e32 v85, 1.0, v91
	v_mul_f32_e64 v91, v9, -v84
	v_mul_f32_e32 v91, 0x3fb8aa3b, v91
	v_mul_f32_e64 v84, v5, -v84
	v_exp_f32_e32 v91, v91
	v_mul_f32_e32 v84, 0x3fb8aa3b, v84
	v_exp_f32_e32 v92, v84
	v_rcp_f32_e32 v84, v85
	v_add_f32_e32 v85, 1.0, v91
	v_rcp_f32_e32 v91, v85
	v_add_f32_e32 v85, 1.0, v92
	v_rcp_f32_e32 v85, v85
	v_lshlrev_b32_e32 v74, 16, v70
	v_and_b32_e32 v75, 0xffff0000, v70
	v_lshlrev_b32_e32 v70, 16, v71
	v_and_b32_e32 v71, 0xffff0000, v71
	v_lshlrev_b32_e32 v76, 16, v72
	v_and_b32_e32 v77, 0xffff0000, v72
	v_lshlrev_b32_e32 v72, 16, v73
	v_and_b32_e32 v73, 0xffff0000, v73
	v_lshlrev_b32_e32 v78, 16, v66
	v_and_b32_e32 v79, 0xffff0000, v66
	v_lshlrev_b32_e32 v66, 16, v67
	v_and_b32_e32 v67, 0xffff0000, v67
	v_lshlrev_b32_e32 v80, 16, v68
	v_and_b32_e32 v81, 0xffff0000, v68
	v_lshlrev_b32_e32 v68, 16, v69
	v_and_b32_e32 v69, 0xffff0000, v69
	v_pk_fma_f32 v[74:75], v[86:87], v[74:75], v[78:79]
	v_pk_fma_f32 v[76:77], v[88:89], v[76:77], v[80:81]
	v_pk_fma_f32 v[70:71], v[90:91], v[70:71], v[66:67]
	v_pk_fma_f32 v[72:73], v[84:85], v[72:73], v[68:69]
	s_mov_b64 s[12:13], -1
	s_and_b64 vcc, exec, s[8:9]
	v_cvt_pk_bf16_f32 v66, v74, v75
	v_cvt_pk_bf16_f32 v67, v70, v71
	v_cvt_pk_bf16_f32 v68, v76, v77
	v_cvt_pk_bf16_f32 v69, v72, v73
	s_cbranch_vccnz .LBB0_1227
	v_add_co_u32_e32 v70, vcc, 0x800000, v82
	s_mov_b64 s[12:13], 0
	s_nop 0
	v_addc_co_u32_e32 v71, vcc, 0, v83, vcc
	global_store_dwordx2 v[70:71], v[66:67], off nt
	global_store_dwordx2 v[70:71], v[68:69], off offset:512 nt
